# attention loop: first QK MFMA issued before the c1 bias adds; scalar look decision and live certification between the MFMAs
# speedup vs baseline: 1.0182x; 1.0018x over previous
.LBB0_310:
	s_cmp_lt_i32 s90, s82
	s_cselect_b64 s[4:5], -1, 0
	s_cmp_lt_u32 s90, 4
	s_cselect_b64 s[2:3], -1, 0
	s_mov_b64 s[12:13], -1
	s_and_b64 vcc, exec, s[2:3]
	s_cbranch_vccnz .LBB0_312
	s_waitcnt lgkmcnt(1)
	v_mfma_f32_32x32x16_bf16 v[130:145], v[158:161], v[166:169], v[2:17]
	v_cndmask_b32_e64 v114, v197, v196, s[4:5]
	v_pk_add_f32 v[128:129], v[114:115], v[16:17] op_sel_hi:[0,1]
	v_pk_add_f32 v[126:127], v[114:115], v[14:15] op_sel_hi:[0,1]
	v_pk_add_f32 v[124:125], v[114:115], v[12:13] op_sel_hi:[0,1]
	v_pk_add_f32 v[122:123], v[114:115], v[10:11] op_sel_hi:[0,1]
	v_pk_add_f32 v[120:121], v[114:115], v[8:9] op_sel_hi:[0,1]
	v_pk_add_f32 v[118:119], v[114:115], v[6:7] op_sel_hi:[0,1]
	v_pk_add_f32 v[116:117], v[114:115], v[4:5] op_sel_hi:[0,1]
	v_pk_add_f32 v[114:115], v[114:115], v[2:3] op_sel_hi:[0,1]
	s_and_b64 s[4:5], s[4:5], exec
	s_cselect_b32 s4, 0, s77
	s_sub_i32 s4, s90, s4
	s_add_i32 s4, s4, -4
	s_cmp_ge_i32 s4, s99
	s_cselect_b64 s[12:13], -1, 0
	s_not_b64 s[4:5], s[12:13]
	v_mfma_f32_32x32x16_bf16 v[114:129], v[150:153], v[166:169], v[114:129]
	v_max3_f32 v246, v98, v97, v105
	v_exp_f32_e32 v246, v246
	s_waitcnt lgkmcnt(0)
	v_mfma_f32_32x32x16_bf16 v[130:145], v[154:157], v[162:165], v[130:145]
	v_mul_f32_e32 v246, 0x4f800000, v246
	v_cmp_ge_f32_e32 vcc, v246, v175
	v_mfma_f32_32x32x16_bf16 v[114:129], v[146:149], v[162:165], v[114:129]
	s_mov_b64 s[80:81], -1
	s_cmp_lg_u64 s[4:5], 0
	s_cbranch_scc1 .LBB0_319
	s_cmp_eq_u32 s99, 0
	s_cbranch_scc1 .Lq_fullA
	s_cmp_lg_u64 vcc, 0
	s_cbranch_scc1 .LBB0_319
	s_branch .Lq_fullA

.Lqk_B_noreads:
	s_cmp_lt_u32 s90, 3
	s_mov_b64 s[2:3], -1
	s_cbranch_scc1 .LBB0_336
	s_waitcnt lgkmcnt(1)
	v_mfma_f32_32x32x16_bf16 v[98:113], v[162:165], v[166:169], v[2:17]
	s_cmp_lt_i32 s12, s82
	s_cselect_b64 vcc, -1, 0
	v_cndmask_b32_e32 v82, v197, v196, vcc
	v_pk_add_f32 v[96:97], v[82:83], v[16:17] op_sel_hi:[0,1]
	v_pk_add_f32 v[94:95], v[82:83], v[14:15] op_sel_hi:[0,1]
	v_pk_add_f32 v[92:93], v[82:83], v[12:13] op_sel_hi:[0,1]
	v_pk_add_f32 v[90:91], v[82:83], v[10:11] op_sel_hi:[0,1]
	v_pk_add_f32 v[88:89], v[82:83], v[8:9] op_sel_hi:[0,1]
	v_pk_add_f32 v[86:87], v[82:83], v[6:7] op_sel_hi:[0,1]
	v_pk_add_f32 v[84:85], v[82:83], v[4:5] op_sel_hi:[0,1]
	v_pk_add_f32 v[82:83], v[82:83], v[2:3] op_sel_hi:[0,1]
	s_nop 1
	v_mfma_f32_32x32x16_bf16 v[82:97], v[150:153], v[166:169], v[82:97]
	s_waitcnt lgkmcnt(0)
	v_mfma_f32_32x32x16_bf16 v[98:113], v[154:157], v[158:161], v[98:113]
	v_mfma_f32_32x32x16_bf16 v[82:97], v[146:149], v[158:161], v[82:97]
	s_branch .LBB0_339
